# P5->P6 seam: own-quad and neighbour-quad counters polled together (one round trip less)
# baseline (speedup 1.0000x reference)
; #define PG8_WAIT_V(n) asm volatile("s_waitcnt vmcnt(" #n ")" ::: "memory")
; #define PG8_BAR __builtin_amdgcn_s_barrier()
; #define SEAM(k) do { if ((k) < 2) xcd_barrier(bar); else xcd_barrier(barg); } while (0)
; template <class Epi, class Sched, bool ALIGN_EPI = false, bool SP2 = false>
; __device__ __forceinline__ void gemm_phase(PG8_LAS unsigned char* lds, const Gemm g, const Sched& S, const Epi& E, volatile PG8_LAS unsigned* sw = nullptr) {
;     ...
;     PG8_WAIT_V(0);
;     if constexpr (!ALIGN_EPI) { if (wr == 0) PG8_BAR; }
;     PG8_BAR;
; __global__ void __launch_bounds__(NWAVES * 64, 2) fwd(Args a) {
;     ...
;     SEAM(5);
.LBB0_562:
	s_setprio 0
	s_waitcnt vmcnt(0)
	s_waitcnt vmcnt(0) lgkmcnt(0)
	s_barrier
	s_and_saveexec_b64 s[0:1], s[90:91]
	v_readlane_b32 s42, v250, 18
	s_xor_b64 s[0:1], exec, s[0:1]
	v_readlane_b32 s43, v250, 19
	s_cbranch_execz .LBB0_615
	s_cmp_lg_u32 s100, 0
	s_cbranch_scc1 .Lq5_slow
	v_readlane_b32 s4, v250, 14
	v_readlane_b32 s5, v250, 15
	s_and_b32 s6, s101, 7
	s_lshl_b32 s6, s6, 3
	s_bfe_u32 s7, s101, 0x30003
	s_or_b32 s6, s6, s7
	s_lshl_b32 s6, s6, 7
	s_add_i32 s6, s6, 0x1d000
	v_mov_b32_e32 v1, s6
	v_mov_b32_e32 v2, 1
	s_mov_b32 s9, 0
	s_nop 4
	global_atomic_add v1, v2, s[4:5]
	buffer_inv sc1
	v_mov_b32_e32 v5, v1
	s_and_b32 s6, s101, 1
	s_lshl_b32 s6, s6, 4
	s_bfe_u32 s7, s101, 0x30003
	s_add_i32 s6, s6, s7
	s_bfe_u32 s7, s101, 0x10007
	s_lshl_b32 s7, s7, 3
	s_add_i32 s6, s6, s7
	s_bfe_u32 s7, s101, 0x10006
	s_lshl_b32 s7, s7, 1
	s_add_i32 s6, s6, s7
	s_add_i32 s6, s6, -1
	s_andn2_b32 s7, s6, 31
	s_cmp_eq_u32 s7, 0
	s_cbranch_scc0 .Lq5_spin
	s_lshr_b32 s7, s6, 4
	s_and_b32 s6, s6, 7
	s_and_b32 s8, s101, 6
	s_or_b32 s7, s7, s8
	s_lshl_b32 s7, s7, 3
	s_or_b32 s6, s6, s7
	s_lshl_b32 s6, s6, 7
	s_add_i32 s6, s6, 0x1d000
	v_mov_b32_e32 v5, s6
.Lq5_spin:
	global_load_dword v3, v1, s[4:5] sc1
	global_load_dword v4, v5, s[4:5] sc1
	s_waitcnt vmcnt(0)
	v_min_u32_e32 v3, v3, v4
	v_cmp_gt_u32_e32 vcc, 4, v3
	s_cbranch_vccz .LBB0_615
	s_sleep 1
	s_add_i32 s9, s9, 1
	s_cmp_lt_u32 s9, 0x2000
	s_cbranch_scc1 .Lq5_spin
	s_branch .LBB0_615
